# v38 with the whole instruction stream shifted by 32 bytes (8 s_nop at entry): code placement trial
# speedup vs baseline: 1.0069x; 1.0069x over previous
; #define LAS __attribute__((address_space(3)))
; __global__ void __launch_bounds__(512, 2) fwd_mega(Args args) {
;     extern __shared__ __attribute__((aligned(16))) unsigned char lds_raw[];
;     LAS unsigned char* lds = (LAS unsigned char*)lds_raw;
;     cg::grid_group grid = cg::this_grid();
;     const int tid = threadIdx.x, lane = tid & 63, wave = __builtin_amdgcn_readfirstlane(tid >> 6);
;     const int G = gridDim.x, bx = blockIdx.x;
;     const float* x = args.in[0]; const float* mem = args.in[1]; const int* positions = (const int*)args.in[2];
;     float* out = args.out;
;     const int lo = args.ph_lo, hi = args.ph_hi;
;     ...
;     if (args.ph_lo < 0) grid.sync();
_Z8fwd_mega4Args:
	s_nop 0
	s_nop 0
	s_nop 0
	s_nop 0
	s_nop 0
	s_nop 0
	s_nop 0
	s_nop 0
	s_mov_b32 s96, s2
	s_load_dwordx4 s[84:87], s[0:1], 0x100
	s_load_dword s2, s[0:1], 0x110
	s_add_u32 s4, s0, 0x108
	s_addc_u32 s5, s1, 0
	v_and_b32_e32 v196, 0x3ff, v0
	s_waitcnt lgkmcnt(0)
	s_cmp_gt_i32 s84, -1
	v_writelane_b32 v249, s2, 0
	s_movk_i32 s2, 0x3ff
	v_readfirstlane_b32 s10, v196
	s_cbranch_scc1 .LBB0_12
	v_lshrrev_b32_e32 v1, 20, v0
	v_lshrrev_b32_e32 v0, 10, v0
	v_or_b32_e32 v0, v0, v1
	v_and_or_b32 v0, v0, s2, v196
	v_cmp_eq_u32_e32 vcc, 0, v0
	s_barrier
	s_and_saveexec_b64 s[2:3], vcc
	s_cbranch_execz .LBB0_11
	buffer_wbl2 sc1
	s_load_dwordx2 s[4:5], s[4:5], 0x58
	s_mov_b64 s[6:7], exec
	v_mbcnt_lo_u32_b32 v0, s6, 0
	v_mbcnt_hi_u32_b32 v0, s7, v0
	v_cmp_eq_u32_e32 vcc, 0, v0
	s_waitcnt lgkmcnt(0)
	s_load_dword s11, s[4:5], 0x28
	s_and_saveexec_b64 s[8:9], vcc
	s_cbranch_execz .LBB0_4
	s_bcnt1_i32_b64 s6, s[6:7]
	v_mov_b32_e32 v1, 0
	v_mov_b32_e32 v2, s6
	global_atomic_add v1, v1, v2, s[4:5] offset:32 sc0
